# D5: big FoX tile loop and NSA selected-branch tile loop get the D4 treatment (next-tile LDS store and next-next-tile global loads issued piecewise between the PV MFMAs, no top-of-loop burst)
# speedup vs baseline: 1.0153x; 1.0075x over previous
.LBB0_659:
	s_add_i32 s0, s6, 1
	s_cmp_lg_u32 s6, 2
	s_cselect_b32 s4, s0, 0
	s_add_i32 s5, s7, 1
.LBB0_667:
	s_cmp_gt_i32 s86, s15
	s_waitcnt lgkmcnt(0)
	s_barrier
	s_cbranch_scc1 .Ld5f_inactive
	s_mulk_i32 s6, 0x4a00
	v_lshl_or_b32 v0, v141, 2, s6
	ds_read_b128 v[2:5], v0 offset:18528
	ds_read_b128 v[6:9], v0 offset:18496
	ds_read_b128 v[10:13], v0 offset:18464
	ds_read_b128 v[48:51], v0 offset:18432
	v_add3_u32 v14, s6, v144, v118
	s_waitcnt lgkmcnt(3)
	v_pk_add_f32 v[60:61], v[136:137], v[2:3] op_sel_hi:[0,1]
	v_pk_add_f32 v[62:63], v[136:137], v[4:5] op_sel_hi:[0,1]
	ds_read_b128 v[2:5], v14
	s_waitcnt lgkmcnt(3)
	v_pk_add_f32 v[56:57], v[136:137], v[6:7] op_sel_hi:[0,1]
	s_waitcnt lgkmcnt(2)
	v_pk_add_f32 v[52:53], v[136:137], v[10:11] op_sel_hi:[0,1]
	s_waitcnt lgkmcnt(1)
	v_pk_add_f32 v[48:49], v[136:137], v[48:49] op_sel_hi:[0,1]
	v_pk_add_f32 v[58:59], v[136:137], v[8:9] op_sel_hi:[0,1]
	v_pk_add_f32 v[54:55], v[136:137], v[12:13] op_sel_hi:[0,1]
	v_pk_add_f32 v[50:51], v[136:137], v[50:51] op_sel_hi:[0,1]
	ds_read_b128 v[6:9], v0 offset:18656
	ds_read_b128 v[10:13], v0 offset:18560
	ds_read_b128 v[64:67], v0 offset:18624
	ds_read_b128 v[68:71], v0 offset:18592
	ds_read_b128 v[150:153], v14 offset:4608
	s_waitcnt lgkmcnt(5)
	v_mfma_f32_32x32x16_bf16 v[48:63], v[2:5], v[80:83], v[48:63]
	ds_read_b128 v[2:5], v14 offset:32
	ds_read_b128 v[236:239], v14 offset:4640
	ds_read_b128 v[240:243], v14 offset:64
	ds_read_b128 v[244:247], v14 offset:4672
	ds_read_b128 v[248:251], v14 offset:96
	s_waitcnt lgkmcnt(9)
	v_add_f32_e64 v76, v136, v6
	v_add_f32_e64 v77, v136, v7
	s_waitcnt lgkmcnt(7)
	v_pk_add_f32 v[72:73], v[136:137], v[64:65] op_sel_hi:[0,1]
	s_waitcnt lgkmcnt(6)
	v_pk_add_f32 v[68:69], v[136:137], v[68:69] op_sel_hi:[0,1]
	v_pk_add_f32 v[64:65], v[136:137], v[10:11] op_sel_hi:[0,1]
	v_pk_add_f32 v[78:79], v[136:137], v[8:9] op_sel_hi:[0,1]
	v_pk_add_f32 v[74:75], v[136:137], v[66:67] op_sel_hi:[0,1]
	v_pk_add_f32 v[70:71], v[136:137], v[70:71] op_sel_hi:[0,1]
	v_pk_add_f32 v[66:67], v[136:137], v[12:13] op_sel_hi:[0,1]
	s_waitcnt lgkmcnt(4)
	v_mfma_f32_32x32x16_bf16 v[48:63], v[2:5], v[84:87], v[48:63]
	ds_read_b128 v[2:5], v14 offset:4704
	s_add_i32 s0, s86, 63
	v_cmp_le_i32_e32 vcc, s0, v116
	s_cmp_eq_u64 vcc, exec
	v_mfma_f32_32x32x16_bf16 v[64:79], v[150:153], v[80:83], v[64:79]
	s_waitcnt lgkmcnt(4)
	v_mfma_f32_32x32x16_bf16 v[64:79], v[236:239], v[84:87], v[64:79]
	s_waitcnt lgkmcnt(3)
	v_mfma_f32_32x32x16_bf16 v[48:63], v[240:243], v[88:91], v[48:63]
	s_waitcnt lgkmcnt(2)
	v_mfma_f32_32x32x16_bf16 v[64:79], v[244:247], v[88:91], v[64:79]
	s_waitcnt lgkmcnt(1)
	v_mfma_f32_32x32x16_bf16 v[48:63], v[248:251], v[92:95], v[48:63]
	s_waitcnt lgkmcnt(0)
	v_mfma_f32_32x32x16_bf16 v[64:79], v[2:5], v[92:95], v[64:79]
	s_cbranch_scc1 .LBB0_672
	v_add_u32_e32 v0, s86, v141
	v_cmp_lt_i32_e32 vcc, v0, v116
	v_add_u32_e32 v2, 2, v0
	s_nop 4
	v_cndmask_b32_e32 v49, v169, v49, vcc
	v_cmp_le_i32_e32 vcc, v0, v116
	s_nop 1
	v_cndmask_b32_e32 v48, v169, v48, vcc
	v_cmp_le_i32_e32 vcc, v2, v116
	v_add_u32_e32 v2, 3, v0
	s_nop 0
	v_cndmask_b32_e32 v50, v169, v50, vcc
	v_cmp_le_i32_e32 vcc, v2, v116
	v_add_u32_e32 v2, 8, v0
	s_nop 0
	v_cndmask_b32_e32 v51, v169, v51, vcc
	v_cmp_le_i32_e32 vcc, v2, v116
	v_add_u32_e32 v2, 9, v0
	s_nop 0
	v_cndmask_b32_e32 v52, v169, v52, vcc
	v_cmp_le_i32_e32 vcc, v2, v116
	v_add_u32_e32 v2, 10, v0
	s_nop 0
	v_cndmask_b32_e32 v53, v169, v53, vcc
	v_cmp_le_i32_e32 vcc, v2, v116
	v_add_u32_e32 v2, 11, v0
	s_nop 0
	v_cndmask_b32_e32 v54, v169, v54, vcc
	v_cmp_le_i32_e32 vcc, v2, v116
	v_add_u32_e32 v2, 16, v0
	s_nop 0
	v_cndmask_b32_e32 v55, v169, v55, vcc
	v_cmp_le_i32_e32 vcc, v2, v116
	v_add_u32_e32 v2, 17, v0
	s_nop 0
	v_cndmask_b32_e32 v56, v169, v56, vcc
	v_cmp_le_i32_e32 vcc, v2, v116
	v_add_u32_e32 v2, 18, v0
	s_nop 0
	v_cndmask_b32_e32 v57, v169, v57, vcc
	v_cmp_le_i32_e32 vcc, v2, v116
	v_add_u32_e32 v2, 19, v0
	s_nop 0
	v_cndmask_b32_e32 v58, v169, v58, vcc
	v_cmp_le_i32_e32 vcc, v2, v116
	v_add_u32_e32 v2, 24, v0
	s_nop 0
	v_cndmask_b32_e32 v59, v169, v59, vcc
	v_cmp_le_i32_e32 vcc, v2, v116
	v_add_u32_e32 v2, 25, v0
	s_nop 0
	v_cndmask_b32_e32 v60, v169, v60, vcc
	v_cmp_le_i32_e32 vcc, v2, v116
	v_add_u32_e32 v2, 26, v0
	s_nop 0
	v_cndmask_b32_e32 v61, v169, v61, vcc
	v_cmp_le_i32_e32 vcc, v2, v116
	v_add_u32_e32 v2, 27, v0
	s_nop 0
	v_cndmask_b32_e32 v62, v169, v62, vcc
	v_cmp_le_i32_e32 vcc, v2, v116
	v_add_u32_e32 v2, 32, v0
	s_nop 0
	v_cndmask_b32_e32 v63, v169, v63, vcc
	v_cmp_le_i32_e32 vcc, v2, v116
	v_add_u32_e32 v2, 33, v0
	s_nop 0
	v_cndmask_b32_e32 v64, v169, v64, vcc
	v_cmp_le_i32_e32 vcc, v2, v116
	v_add_u32_e32 v2, 34, v0
	s_nop 0
	v_cndmask_b32_e32 v65, v169, v65, vcc
	v_cmp_le_i32_e32 vcc, v2, v116
	v_add_u32_e32 v2, 35, v0
	s_nop 0
	v_cndmask_b32_e32 v66, v169, v66, vcc
	v_cmp_le_i32_e32 vcc, v2, v116
	v_add_u32_e32 v2, 40, v0
	s_nop 0
	v_cndmask_b32_e32 v67, v169, v67, vcc
	v_cmp_le_i32_e32 vcc, v2, v116
	v_add_u32_e32 v2, 41, v0
	s_nop 0
	v_cndmask_b32_e32 v68, v169, v68, vcc
	v_cmp_le_i32_e32 vcc, v2, v116
	v_add_u32_e32 v2, 42, v0
	s_nop 0
	v_cndmask_b32_e32 v69, v169, v69, vcc
	v_cmp_le_i32_e32 vcc, v2, v116
	v_add_u32_e32 v2, 43, v0
	s_nop 0
	v_cndmask_b32_e32 v70, v169, v70, vcc
	v_cmp_le_i32_e32 vcc, v2, v116
	v_add_u32_e32 v2, 48, v0
	s_nop 0
	v_cndmask_b32_e32 v71, v169, v71, vcc
	v_cmp_le_i32_e32 vcc, v2, v116
	v_add_u32_e32 v2, 49, v0
	s_nop 0
	v_cndmask_b32_e32 v72, v169, v72, vcc
	v_cmp_le_i32_e32 vcc, v2, v116
	v_add_u32_e32 v2, 50, v0
	s_nop 0
	v_cndmask_b32_e32 v73, v169, v73, vcc
	v_cmp_le_i32_e32 vcc, v2, v116
	v_add_u32_e32 v2, 51, v0
	s_nop 0
	v_cndmask_b32_e32 v74, v169, v74, vcc
	v_cmp_le_i32_e32 vcc, v2, v116
	v_add_u32_e32 v2, 56, v0
	s_nop 0
	v_cndmask_b32_e32 v75, v169, v75, vcc
	v_cmp_le_i32_e32 vcc, v2, v116
	v_add_u32_e32 v2, 57, v0
	s_nop 0
	v_cndmask_b32_e32 v76, v169, v76, vcc
	v_cmp_le_i32_e32 vcc, v2, v116
	v_add_u32_e32 v2, 58, v0
	v_add_u32_e32 v0, 59, v0
	v_cndmask_b32_e32 v77, v169, v77, vcc
	v_cmp_le_i32_e32 vcc, v2, v116
	s_nop 1
	v_cndmask_b32_e32 v78, v169, v78, vcc
	v_cmp_gt_i32_e32 vcc, v0, v116
	s_and_saveexec_b64 s[0:1], vcc
	v_mov_b32_e32 v79, 0xf149f2ca
	s_or_b64 exec, exec, s[0:1]
.LBB0_672:
	s_nop 7
	v_exp_f32_e32 v2, v48
	v_exp_f32_e32 v3, v49
	v_exp_f32_e32 v4, v50
	v_exp_f32_e32 v5, v51
	v_add_f32_e32 v0, 0, v2
	v_exp_f32_e32 v6, v52
	v_add_f32_e32 v0, v3, v0
	v_exp_f32_e32 v7, v53
	v_add_f32_e32 v0, v4, v0
	v_exp_f32_e32 v8, v54
	v_add_f32_e32 v0, v5, v0
	v_exp_f32_e32 v9, v55
	v_add_f32_e32 v0, v6, v0
	v_add_f32_e32 v0, v7, v0
	v_exp_f32_e32 v50, v60
	v_exp_f32_e32 v60, v70
	v_add3_u32 v70, s6, v143, v145
	v_add_f32_e32 v0, v8, v0
	v_exp_f32_e32 v51, v61
	v_exp_f32_e32 v61, v71
	v_add_u32_e32 v71, 0x2000, v70
	v_add_f32_e32 v0, v9, v0
	v_cvt_pk_bf16_f32 v2, v2, v3
	v_cvt_pk_bf16_f32 v3, v4, v5
	v_cvt_pk_bf16_f32 v4, v6, v7
	v_cvt_pk_bf16_f32 v5, v8, v9
	ds_read2_b64 v[6:9], v71 offset0:128 offset1:130
	ds_read2_b64 v[10:13], v71 offset0:132 offset1:134
	v_add_u32_e32 v70, 0x3000, v70
	s_waitcnt lgkmcnt(1)
	v_mfma_f32_32x32x16_bf16 v[32:47], v[6:9], v[2:5], v[32:47]
	s_mul_i32 s16, s4, 0x4a00
	v_or_b32_e32 v252, s16, v125
	v_add_u32_e32 v253, v252, v137
	s_waitcnt vmcnt(3)
	ds_write_b128 v253, v[100:103]
	global_load_dwordx4 v[100:103], v228, s[10:11]
	ds_read2_b64 v[6:9], v70 offset0:160 offset1:162
	v_exp_f32_e32 v14, v56
	v_exp_f32_e32 v15, v57
	v_exp_f32_e32 v48, v58
	v_exp_f32_e32 v49, v59
	v_exp_f32_e32 v52, v62
	v_exp_f32_e32 v53, v63
	s_waitcnt lgkmcnt(0)
	v_mfma_f32_32x32x16_bf16 v[16:31], v[6:9], v[2:5], v[16:31]
	ds_read2_b64 v[6:9], v70 offset0:164 offset1:166
	v_cvt_pk_bf16_f32 v2, v14, v15
	v_cvt_pk_bf16_f32 v3, v48, v49
	v_cvt_pk_bf16_f32 v4, v50, v51
	v_cvt_pk_bf16_f32 v5, v52, v53
	v_exp_f32_e32 v54, v64
	v_exp_f32_e32 v55, v65
	s_waitcnt lgkmcnt(0)
	v_mfma_f32_32x32x16_bf16 v[16:31], v[6:9], v[2:5], v[16:31]
	v_add3_u32 v253, v252, v138, s33
	s_waitcnt vmcnt(2)
	ds_write2_b64 v253, v[104:105], v[106:107] offset1:1
	global_load_dwordx4 v[104:107], v230, s[22:23]
	ds_read2_b64 v[6:9], v71 offset0:136 offset1:138
	v_exp_f32_e32 v56, v66
	v_exp_f32_e32 v57, v67
	v_exp_f32_e32 v58, v68
	v_exp_f32_e32 v59, v69
	v_add_f32_e32 v0, v14, v0
	v_add_f32_e32 v0, v15, v0
	v_mfma_f32_32x32x16_bf16 v[32:47], v[10:13], v[2:5], v[32:47]
	v_cvt_pk_bf16_f32 v2, v54, v55
	v_cvt_pk_bf16_f32 v3, v56, v57
	v_cvt_pk_bf16_f32 v4, v58, v59
	v_cvt_pk_bf16_f32 v5, v60, v61
	v_add_f32_e32 v0, v48, v0
	v_add_f32_e32 v0, v49, v0
	v_exp_f32_e32 v62, v72
	s_waitcnt lgkmcnt(0)
	v_mfma_f32_32x32x16_bf16 v[32:47], v[6:9], v[2:5], v[32:47]
	v_add_u32_e32 v253, v252, v139
	s_waitcnt vmcnt(3)
	ds_write_b128 v253, v[108:111]
	global_load_dwordx4 v[108:111], v229, s[10:11]
	ds_read2_b64 v[6:9], v70 offset0:168 offset1:170
	v_exp_f32_e32 v63, v73
	v_exp_f32_e32 v64, v74
	v_exp_f32_e32 v65, v75
	v_exp_f32_e32 v66, v76
	v_exp_f32_e32 v67, v77
	v_exp_f32_e32 v68, v78
	s_waitcnt lgkmcnt(0)
	v_mfma_f32_32x32x16_bf16 v[16:31], v[6:9], v[2:5], v[16:31]
	ds_read2_b64 v[6:9], v71 offset0:140 offset1:142
	v_exp_f32_e32 v69, v79
	v_add_f32_e32 v0, v50, v0
	v_add_f32_e32 v0, v51, v0
	v_add_f32_e32 v0, v52, v0
	v_add_f32_e32 v0, v53, v0
	v_cvt_pk_bf16_f32 v2, v62, v63
	v_cvt_pk_bf16_f32 v3, v64, v65
	v_cvt_pk_bf16_f32 v4, v66, v67
	v_cvt_pk_bf16_f32 v5, v68, v69
	v_add_f32_e32 v0, v54, v0
	v_add_f32_e32 v0, v55, v0
	s_waitcnt lgkmcnt(0)
	v_mfma_f32_32x32x16_bf16 v[32:47], v[6:9], v[2:5], v[32:47]
	v_add3_u32 v253, v252, v140, s33
	s_waitcnt vmcnt(3)
	ds_write2_b64 v253, v[112:113], v[114:115] offset1:1
	global_load_dwordx4 v[112:115], v231, s[22:23]
	s_add_u32 s10, s10, 0x2000
	s_addc_u32 s11, s11, 0
	s_add_u32 s22, s22, 0x80
	s_addc_u32 s23, s23, 0
	ds_read2_b64 v[6:9], v70 offset0:172 offset1:174
	v_add_f32_e32 v0, v56, v0
	v_add_f32_e32 v0, v57, v0
	v_add_f32_e32 v0, v58, v0
	v_add_f32_e32 v0, v59, v0
	v_add_f32_e32 v0, v60, v0
	v_add_f32_e32 v0, v61, v0
	v_add_f32_e32 v0, v62, v0
	v_add_f32_e32 v0, v63, v0
	s_waitcnt lgkmcnt(0)
	v_mfma_f32_32x32x16_bf16 v[16:31], v[6:9], v[2:5], v[16:31]
	s_and_saveexec_b64 s[0:1], s[38:39]
	s_cbranch_execz .Ld5f_noga
	s_waitcnt vmcnt(4)
	v_xor_b32_e32 v239, 0x80000000, v99
	v_xor_b32_e32 v238, 0x80000000, v98
	v_xor_b32_e32 v237, 0x80000000, v97
	v_xor_b32_e32 v236, 0x80000000, v96
	v_add_u32_e32 v253, s16, v119
	ds_write_b128 v253, v[236:239] offset:18432
	global_load_dwordx4 v[96:99], v228, s[24:25]
.Ld5f_noga:
	s_or_b64 exec, exec, s[0:1]
	s_add_u32 s24, s24, 0x100
	s_addc_u32 s25, s25, 0
	v_add_f32_e32 v0, v64, v0
	v_add_f32_e32 v0, v65, v0
	v_add_f32_e32 v0, v66, v0
	v_add_f32_e32 v0, v67, v0
	v_add_f32_e32 v0, v68, v0
	v_add_f32_e32 v0, v69, v0
	v_add_f32_e32 v142, v142, v0
	v_cmp_lt_f32_e32 vcc, s20, v0
	s_cbranch_vccz .LBB0_674
	v_mov_b32_e32 v2, v0
	s_nop 1
	v_permlane32_swap_b32_e32 v0, v2
	v_add_f32_e32 v0, v0, v2
	v_log_f32_e32 v2, v0
	v_cmp_lt_f32_e32 vcc, s20, v0
	s_nop 1
	v_cndmask_b32_e32 v2, 0, v2, vcc
	v_exp_f32_e64 v0, -v2
	v_add_f32_e32 v148, v148, v2
	v_xor_b32_e32 v136, 0x80000000, v148
	v_mul_f32_e32 v142, v142, v0
	v_pk_mul_f32 v[46:47], v[46:47], v[0:1] op_sel_hi:[1,0]
	v_pk_mul_f32 v[44:45], v[44:45], v[0:1] op_sel_hi:[1,0]
	v_pk_mul_f32 v[42:43], v[42:43], v[0:1] op_sel_hi:[1,0]
	v_pk_mul_f32 v[40:41], v[40:41], v[0:1] op_sel_hi:[1,0]
	v_pk_mul_f32 v[38:39], v[38:39], v[0:1] op_sel_hi:[1,0]
	v_pk_mul_f32 v[36:37], v[36:37], v[0:1] op_sel_hi:[1,0]
	v_pk_mul_f32 v[34:35], v[34:35], v[0:1] op_sel_hi:[1,0]
	v_pk_mul_f32 v[32:33], v[32:33], v[0:1] op_sel_hi:[1,0]
	v_pk_mul_f32 v[30:31], v[30:31], v[0:1] op_sel_hi:[1,0]
	v_pk_mul_f32 v[28:29], v[28:29], v[0:1] op_sel_hi:[1,0]
	v_pk_mul_f32 v[26:27], v[26:27], v[0:1] op_sel_hi:[1,0]
	v_pk_mul_f32 v[24:25], v[24:25], v[0:1] op_sel_hi:[1,0]
	v_pk_mul_f32 v[22:23], v[22:23], v[0:1] op_sel_hi:[1,0]
	v_pk_mul_f32 v[20:21], v[20:21], v[0:1] op_sel_hi:[1,0]
	v_pk_mul_f32 v[18:19], v[18:19], v[0:1] op_sel_hi:[1,0]
	v_pk_mul_f32 v[16:17], v[16:17], v[0:1] op_sel_hi:[1,0]
	s_branch .LBB0_674
.Ld5f_inactive:
	s_mul_i32 s16, s4, 0x4a00
	v_or_b32_e32 v252, s16, v125
	v_add_u32_e32 v253, v252, v137
	s_waitcnt vmcnt(3)
	ds_write_b128 v253, v[100:103]
	global_load_dwordx4 v[100:103], v228, s[10:11]
	v_add3_u32 v253, v252, v138, s33
	s_waitcnt vmcnt(2)
	ds_write2_b64 v253, v[104:105], v[106:107] offset1:1
	global_load_dwordx4 v[104:107], v230, s[22:23]
	v_add_u32_e32 v253, v252, v139
	s_waitcnt vmcnt(3)
	ds_write_b128 v253, v[108:111]
	global_load_dwordx4 v[108:111], v229, s[10:11]
	v_add3_u32 v253, v252, v140, s33
	s_waitcnt vmcnt(3)
	ds_write2_b64 v253, v[112:113], v[114:115] offset1:1
	global_load_dwordx4 v[112:115], v231, s[22:23]
	s_add_u32 s10, s10, 0x2000
	s_addc_u32 s11, s11, 0
	s_add_u32 s22, s22, 0x80
	s_addc_u32 s23, s23, 0
	s_and_saveexec_b64 s[0:1], s[38:39]
	s_cbranch_execz .Ld5f_nogb
	s_waitcnt vmcnt(4)
	v_xor_b32_e32 v239, 0x80000000, v99
	v_xor_b32_e32 v238, 0x80000000, v98
	v_xor_b32_e32 v237, 0x80000000, v97
	v_xor_b32_e32 v236, 0x80000000, v96
	v_add_u32_e32 v253, s16, v119
	ds_write_b128 v253, v[236:239] offset:18432
	global_load_dwordx4 v[96:99], v228, s[24:25]
.Ld5f_nogb:
	s_or_b64 exec, exec, s[0:1]
	s_add_u32 s24, s24, 0x100
	s_addc_u32 s25, s25, 0

.Ld5f_exit:
	s_waitcnt vmcnt(0)
	s_branch .LBB0_690

.LBB0_905:
	s_add_i32 s1, s0, 1
	s_cmp_lg_u32 s0, 2
	s_cselect_b32 s17, s1, 0
.LBB0_909:
	s_cmp_gt_i32 s15, s14
	s_waitcnt lgkmcnt(0)
	s_barrier
	s_cbranch_scc1 .Ld5s_inactive
	s_lshr_b32 s1, s16, 3
	s_and_b32 s1, s1, 0x1ffffffc
	v_add_u32_e32 v50, s1, v114
	ds_read_b32 v50, v50
	s_and_b32 s1, s16, 31
	s_waitcnt lgkmcnt(0)
	v_bfe_u32 v51, v50, s1, 1
	v_cmp_ne_u32_e32 vcc, 0, v51
	s_cbranch_vccz .Ld5s_inactive
	s_mul_i32 s22, s0, 0x4a00
	v_add3_u32 v193, s22, v182, v130
	v_lshrrev_b32_e32 v147, s1, v50
	ds_read_b128 v[148:151], v193 offset:4608
	ds_read_b128 v[50:53], v193
	ds_read_b128 v[152:155], v193 offset:32
	ds_read_b128 v[236:239], v193 offset:4640
	ds_read_b128 v[240:243], v193 offset:64
	ds_read_b128 v[244:247], v193 offset:4672
	ds_read_b128 v[248:251], v193 offset:96
	s_add_i32 s23, s15, 63
	v_cmp_le_i32_e32 vcc, s23, v128
	s_waitcnt lgkmcnt(5)
	v_mfma_f32_32x32x16_bf16 v[66:81], v[50:53], v[82:85], v[34:49]
	s_waitcnt lgkmcnt(4)
	v_mfma_f32_32x32x16_bf16 v[66:81], v[152:155], v[86:89], v[66:81]
	ds_read_b128 v[152:155], v193 offset:4704
	v_and_b32_e32 v147, 1, v147
	s_cmp_lg_u64 vcc, exec
	s_mov_b64 s[0:1], -1
	v_cmp_eq_u32_e32 vcc, 1, v147
	s_mov_b64 s[4:5], -1
	v_mfma_f32_32x32x16_bf16 v[50:65], v[148:151], v[82:85], v[34:49]
	s_waitcnt lgkmcnt(4)
	v_mfma_f32_32x32x16_bf16 v[50:65], v[236:239], v[86:89], v[50:65]
	s_waitcnt lgkmcnt(3)
	v_mfma_f32_32x32x16_bf16 v[66:81], v[240:243], v[90:93], v[66:81]
	s_waitcnt lgkmcnt(2)
	v_mfma_f32_32x32x16_bf16 v[50:65], v[244:247], v[90:93], v[50:65]
	s_waitcnt lgkmcnt(1)
	v_mfma_f32_32x32x16_bf16 v[66:81], v[248:251], v[94:97], v[66:81]
	s_waitcnt lgkmcnt(0)
	v_mfma_f32_32x32x16_bf16 v[50:65], v[152:155], v[94:97], v[50:65]
	s_cbranch_scc0 .LBB0_917
	v_cndmask_b32_e32 v148, -1, v128, vcc
	v_cmp_le_i32_e32 vcc, s23, v148
	s_cmp_eq_u64 vcc, exec
	s_cbranch_scc1 .LBB0_916
	v_add_u32_e32 v149, s15, v125
	v_cmp_lt_i32_e32 vcc, v149, v148
	v_add_u32_e32 v150, 2, v149
	s_nop 2
	v_cndmask_b32_e32 v67, v169, v67, vcc
	v_cmp_le_i32_e32 vcc, v149, v148
	s_nop 1
	v_cndmask_b32_e32 v66, v169, v66, vcc
	v_cmp_le_i32_e32 vcc, v150, v148
	v_add_u32_e32 v150, 3, v149
	s_nop 0
	v_cndmask_b32_e32 v68, v169, v68, vcc
	v_cmp_le_i32_e32 vcc, v150, v148
	v_add_u32_e32 v150, 8, v149
	s_nop 0
	v_cndmask_b32_e32 v69, v169, v69, vcc
	v_cmp_le_i32_e32 vcc, v150, v148
	v_add_u32_e32 v150, 9, v149
	s_nop 0
	v_cndmask_b32_e32 v70, v169, v70, vcc
	v_cmp_le_i32_e32 vcc, v150, v148
	v_add_u32_e32 v150, 10, v149
	s_nop 0
	v_cndmask_b32_e32 v71, v169, v71, vcc
	v_cmp_le_i32_e32 vcc, v150, v148
	v_add_u32_e32 v150, 11, v149
	s_nop 0
	v_cndmask_b32_e32 v72, v169, v72, vcc
	v_cmp_le_i32_e32 vcc, v150, v148
	v_add_u32_e32 v150, 16, v149
	s_nop 0
	v_cndmask_b32_e32 v73, v169, v73, vcc
	v_cmp_le_i32_e32 vcc, v150, v148
	v_add_u32_e32 v150, 17, v149
	s_nop 0
	v_cndmask_b32_e32 v74, v169, v74, vcc
	v_cmp_le_i32_e32 vcc, v150, v148
	v_add_u32_e32 v150, 18, v149
	s_nop 0
	v_cndmask_b32_e32 v75, v169, v75, vcc
	v_cmp_le_i32_e32 vcc, v150, v148
	v_add_u32_e32 v150, 19, v149
	s_nop 0
	v_cndmask_b32_e32 v76, v169, v76, vcc
	v_cmp_le_i32_e32 vcc, v150, v148
	v_add_u32_e32 v150, 24, v149
	s_nop 0
	v_cndmask_b32_e32 v77, v169, v77, vcc
	v_cmp_le_i32_e32 vcc, v150, v148
	v_add_u32_e32 v150, 25, v149
	s_nop 0
	v_cndmask_b32_e32 v78, v169, v78, vcc
	v_cmp_le_i32_e32 vcc, v150, v148
	v_add_u32_e32 v150, 26, v149
	s_nop 0
	v_cndmask_b32_e32 v79, v169, v79, vcc
	v_cmp_le_i32_e32 vcc, v150, v148
	v_add_u32_e32 v150, 27, v149
	s_nop 0
	v_cndmask_b32_e32 v80, v169, v80, vcc
	v_cmp_le_i32_e32 vcc, v150, v148
	v_add_u32_e32 v150, 32, v149
	s_nop 0
	v_cndmask_b32_e32 v81, v169, v81, vcc
	v_cmp_le_i32_e32 vcc, v150, v148
	v_add_u32_e32 v150, 33, v149
	s_nop 0
	v_cndmask_b32_e32 v50, v169, v50, vcc
	v_cmp_le_i32_e32 vcc, v150, v148
	v_add_u32_e32 v150, 34, v149
	s_nop 0
	v_cndmask_b32_e32 v51, v169, v51, vcc
	v_cmp_le_i32_e32 vcc, v150, v148
	v_add_u32_e32 v150, 35, v149
	s_nop 0
	v_cndmask_b32_e32 v52, v169, v52, vcc
	v_cmp_le_i32_e32 vcc, v150, v148
	v_add_u32_e32 v150, 40, v149
	s_nop 0
	v_cndmask_b32_e32 v53, v169, v53, vcc
	v_cmp_le_i32_e32 vcc, v150, v148
	v_add_u32_e32 v150, 41, v149
	s_nop 0
	v_cndmask_b32_e32 v54, v169, v54, vcc
	v_cmp_le_i32_e32 vcc, v150, v148
	v_add_u32_e32 v150, 42, v149
	s_nop 0
	v_cndmask_b32_e32 v55, v169, v55, vcc
	v_cmp_le_i32_e32 vcc, v150, v148
	v_add_u32_e32 v150, 43, v149
	s_nop 0
	v_cndmask_b32_e32 v56, v169, v56, vcc
	v_cmp_le_i32_e32 vcc, v150, v148
	v_add_u32_e32 v150, 48, v149
	s_nop 0
	v_cndmask_b32_e32 v57, v169, v57, vcc
	v_cmp_le_i32_e32 vcc, v150, v148
	v_add_u32_e32 v150, 49, v149
	s_nop 0
	v_cndmask_b32_e32 v58, v169, v58, vcc
	v_cmp_le_i32_e32 vcc, v150, v148
	v_add_u32_e32 v150, 50, v149
	s_nop 0
	v_cndmask_b32_e32 v59, v169, v59, vcc
	v_cmp_le_i32_e32 vcc, v150, v148
	v_add_u32_e32 v150, 51, v149
	s_nop 0
	v_cndmask_b32_e32 v60, v169, v60, vcc
	v_cmp_le_i32_e32 vcc, v150, v148
	v_add_u32_e32 v150, 56, v149
	s_nop 0
	v_cndmask_b32_e32 v61, v169, v61, vcc
	v_cmp_le_i32_e32 vcc, v150, v148
	v_add_u32_e32 v150, 57, v149
	s_nop 0
	v_cndmask_b32_e32 v62, v169, v62, vcc
	v_cmp_le_i32_e32 vcc, v150, v148
	v_add_u32_e32 v150, 58, v149
	v_add_u32_e32 v149, 59, v149
	v_cndmask_b32_e32 v63, v169, v63, vcc
	v_cmp_le_i32_e32 vcc, v150, v148
	s_nop 1
	v_cndmask_b32_e32 v64, v169, v64, vcc
	v_cmp_gt_i32_e32 vcc, v149, v148
	s_and_saveexec_b64 s[4:5], vcc
	v_mov_b32_e32 v65, 0xf149f2ca
	s_or_b64 exec, exec, s[4:5]

.LBB0_919:
	s_nop 7
	v_exp_f32_e32 v66, v66
	v_exp_f32_e32 v67, v67
	v_exp_f32_e32 v68, v68
	v_exp_f32_e32 v69, v69
	v_add_f32_e32 v147, 0, v66
	v_exp_f32_e32 v70, v70
	v_add_f32_e32 v147, v67, v147
	v_exp_f32_e32 v71, v71
	v_add_f32_e32 v147, v68, v147
	v_exp_f32_e32 v72, v72
	v_add_f32_e32 v147, v69, v147
	v_exp_f32_e32 v73, v73
	v_add_f32_e32 v147, v70, v147
	v_exp_f32_e32 v74, v74
	v_add_f32_e32 v147, v71, v147
	v_exp_f32_e32 v75, v75
	v_add_f32_e32 v147, v72, v147
	v_exp_f32_e32 v76, v76
	v_add_f32_e32 v147, v73, v147
	v_exp_f32_e32 v77, v77
	v_add_f32_e32 v147, v74, v147
	v_exp_f32_e32 v78, v78
	v_add_f32_e32 v147, v75, v147
	v_exp_f32_e32 v79, v79
	v_add_f32_e32 v147, v76, v147
	v_exp_f32_e32 v80, v80
	v_add_f32_e32 v147, v77, v147
	v_exp_f32_e32 v81, v81
	v_add_f32_e32 v147, v78, v147
	v_exp_f32_e32 v148, v50
	v_add_f32_e32 v147, v79, v147
	v_exp_f32_e32 v149, v51
	v_add_f32_e32 v50, v80, v147
	v_add_f32_e32 v50, v81, v50
	v_add3_u32 v153, s22, v181, v187
	v_add_f32_e32 v50, v148, v50
	v_add_u32_e32 v154, 0x2000, v153
	v_add_f32_e32 v147, v149, v50
	v_exp_f32_e32 v150, v52
	v_exp_f32_e32 v151, v53
	ds_read2_b64 v[50:53], v154 offset0:128 offset1:130
	v_add_u32_e32 v153, 0x3000, v153
	v_exp_f32_e32 v152, v54
	v_cvt_pk_bf16_f32 v54, v66, v67
	v_cvt_pk_bf16_f32 v66, v68, v69
	v_cvt_pk_bf16_f32 v67, v70, v71
	v_cvt_pk_bf16_f32 v68, v72, v73
	ds_read2_b64 v[70:73], v153 offset0:160 offset1:162
	v_cndmask_b32_e64 v69, 0, v68, s[0:1]
	v_cndmask_b32_e64 v68, 0, v67, s[0:1]
	v_cndmask_b32_e64 v67, 0, v66, s[0:1]
	v_cndmask_b32_e64 v66, 0, v54, s[0:1]
	v_exp_f32_e32 v155, v55
	v_exp_f32_e32 v193, v56
	s_waitcnt lgkmcnt(1)
	v_mfma_f32_32x32x16_bf16 v[18:33], v[50:53], v[66:69], v[18:33]
	s_mul_i32 s23, s17, 0x4a00
	v_or_b32_e32 v252, s23, v129
	v_add_u32_e32 v253, v252, v131
	s_waitcnt vmcnt(3)
	ds_write_b128 v253, v[98:101]
	global_load_dwordx4 v[98:101], v228, s[12:13]
	v_add_f32_e32 v50, v150, v147
	v_add_f32_e32 v50, v151, v50
	v_add_f32_e32 v147, v152, v50
	ds_read2_b64 v[50:53], v154 offset0:132 offset1:134
	v_exp_f32_e32 v194, v57
	v_cvt_pk_bf16_f32 v54, v74, v75
	v_cvt_pk_bf16_f32 v55, v76, v77
	s_waitcnt lgkmcnt(1)
	v_mfma_f32_32x32x16_bf16 v[2:17], v[70:73], v[66:69], v[2:17]
	ds_read2_b64 v[66:69], v153 offset0:164 offset1:166
	v_cvt_pk_bf16_f32 v56, v78, v79
	v_cvt_pk_bf16_f32 v57, v80, v81
	v_cndmask_b32_e64 v57, 0, v57, s[0:1]
	v_cndmask_b32_e64 v56, 0, v56, s[0:1]
	v_cndmask_b32_e64 v55, 0, v55, s[0:1]
	v_cndmask_b32_e64 v54, 0, v54, s[0:1]
	v_exp_f32_e32 v58, v58
	v_exp_f32_e32 v59, v59
	s_waitcnt lgkmcnt(1)
	v_mfma_f32_32x32x16_bf16 v[18:33], v[50:53], v[54:57], v[18:33]
	v_add3_u32 v253, v252, v185, s33
	s_waitcnt vmcnt(2)
	ds_write2_b64 v253, v[102:103], v[104:105] offset1:1
	global_load_dwordx4 v[102:105], v230, s[24:25]
	v_add_f32_e32 v50, v155, v147
	v_add_f32_e32 v50, v193, v50
	v_add_f32_e32 v50, v194, v50
	v_add_f32_e32 v70, v58, v50
	ds_read2_b64 v[50:53], v154 offset0:136 offset1:138
	v_exp_f32_e32 v60, v60
	v_exp_f32_e32 v71, v61
	s_waitcnt lgkmcnt(1)
	v_mfma_f32_32x32x16_bf16 v[2:17], v[66:69], v[54:57], v[2:17]
	ds_read2_b64 v[66:69], v153 offset0:168 offset1:170
	v_cvt_pk_bf16_f32 v54, v148, v149
	v_cvt_pk_bf16_f32 v55, v150, v151
	v_cvt_pk_bf16_f32 v56, v152, v155
	v_cvt_pk_bf16_f32 v57, v193, v194
	v_cndmask_b32_e64 v57, 0, v57, s[0:1]
	v_cndmask_b32_e64 v56, 0, v56, s[0:1]
	v_cndmask_b32_e64 v55, 0, v55, s[0:1]
	v_cndmask_b32_e64 v54, 0, v54, s[0:1]
	v_exp_f32_e32 v62, v62
	v_exp_f32_e32 v63, v63
	s_waitcnt lgkmcnt(1)
	v_mfma_f32_32x32x16_bf16 v[18:33], v[50:53], v[54:57], v[18:33]
	v_add_u32_e32 v253, v252, v180
	s_waitcnt vmcnt(3)
	ds_write_b128 v253, v[106:109]
	global_load_dwordx4 v[106:109], v229, s[12:13]
	v_add_f32_e32 v50, v59, v70
	v_add_f32_e32 v70, v60, v50
	ds_read2_b64 v[50:53], v154 offset0:140 offset1:142
	v_exp_f32_e32 v64, v64
	v_exp_f32_e32 v65, v65
	s_waitcnt lgkmcnt(1)
	v_mfma_f32_32x32x16_bf16 v[2:17], v[66:69], v[54:57], v[2:17]
	v_cvt_pk_bf16_f32 v54, v58, v59
	v_cvt_pk_bf16_f32 v55, v60, v71
	ds_read2_b64 v[58:61], v153 offset0:172 offset1:174
	v_cvt_pk_bf16_f32 v56, v62, v63
	v_cvt_pk_bf16_f32 v57, v64, v65
	v_cndmask_b32_e64 v57, 0, v57, s[0:1]
	v_cndmask_b32_e64 v56, 0, v56, s[0:1]
	v_cndmask_b32_e64 v55, 0, v55, s[0:1]
	v_cndmask_b32_e64 v54, 0, v54, s[0:1]
	s_waitcnt lgkmcnt(1)
	s_nop 0
	v_mfma_f32_32x32x16_bf16 v[18:33], v[50:53], v[54:57], v[18:33]
	v_add3_u32 v253, v252, v186, s33
	s_waitcnt vmcnt(3)
	ds_write2_b64 v253, v[110:111], v[112:113] offset1:1
	global_load_dwordx4 v[110:113], v231, s[24:25]
	s_add_u32 s12, s12, 0x2000
	s_addc_u32 s13, s13, 0
	s_add_u32 s24, s24, 0x80
	s_addc_u32 s25, s25, 0
	v_add_f32_e32 v50, v71, v70
	v_add_f32_e32 v50, v62, v50
	v_add_f32_e32 v50, v63, v50
	v_add_f32_e32 v50, v64, v50
	v_add_f32_e32 v50, v65, v50
	v_cndmask_b32_e64 v50, 0, v50, s[0:1]
	v_add_f32_e32 v133, v133, v50
	s_waitcnt lgkmcnt(0)
	v_mfma_f32_32x32x16_bf16 v[2:17], v[58:61], v[54:57], v[2:17]
	v_cmp_lt_f32_e32 vcc, s20, v50
	s_cbranch_vccz .LBB0_921
	v_mov_b32_e32 v34, v50
	s_nop 1
	v_permlane32_swap_b32_e32 v50, v34
	v_add_f32_e32 v34, v50, v34
	v_log_f32_e32 v35, v34
	v_cmp_lt_f32_e32 vcc, s20, v34
	s_nop 1
	v_cndmask_b32_e32 v35, 0, v35, vcc
	v_exp_f32_e64 v34, -v35
	v_add_f32_e32 v135, v135, v35
	v_xor_b32_e32 v49, 0x80000000, v135
	v_mov_b32_e32 v48, v49
	v_mul_f32_e32 v133, v133, v34
	v_pk_mul_f32 v[32:33], v[32:33], v[34:35] op_sel_hi:[1,0]
	v_pk_mul_f32 v[30:31], v[30:31], v[34:35] op_sel_hi:[1,0]
	v_pk_mul_f32 v[28:29], v[28:29], v[34:35] op_sel_hi:[1,0]
	v_pk_mul_f32 v[26:27], v[26:27], v[34:35] op_sel_hi:[1,0]
	v_pk_mul_f32 v[24:25], v[24:25], v[34:35] op_sel_hi:[1,0]
	v_pk_mul_f32 v[22:23], v[22:23], v[34:35] op_sel_hi:[1,0]
	v_pk_mul_f32 v[20:21], v[20:21], v[34:35] op_sel_hi:[1,0]
	v_pk_mul_f32 v[18:19], v[18:19], v[34:35] op_sel_hi:[1,0]
	v_pk_mul_f32 v[16:17], v[16:17], v[34:35] op_sel_hi:[1,0]
	v_pk_mul_f32 v[14:15], v[14:15], v[34:35] op_sel_hi:[1,0]
	v_pk_mul_f32 v[12:13], v[12:13], v[34:35] op_sel_hi:[1,0]
	v_pk_mul_f32 v[10:11], v[10:11], v[34:35] op_sel_hi:[1,0]
	v_pk_mul_f32 v[8:9], v[8:9], v[34:35] op_sel_hi:[1,0]
	v_pk_mul_f32 v[6:7], v[6:7], v[34:35] op_sel_hi:[1,0]
	v_pk_mul_f32 v[4:5], v[4:5], v[34:35] op_sel_hi:[1,0]
	v_pk_mul_f32 v[2:3], v[2:3], v[34:35] op_sel_hi:[1,0]
	v_mov_b32_e32 v47, v49
	v_mov_b32_e32 v46, v49
	v_mov_b32_e32 v45, v49
	v_mov_b32_e32 v44, v49
	v_mov_b32_e32 v43, v49
	v_mov_b32_e32 v42, v49
	v_mov_b32_e32 v41, v49
	v_mov_b32_e32 v40, v49
	v_mov_b32_e32 v39, v49
	v_mov_b32_e32 v38, v49
	v_mov_b32_e32 v37, v49
	v_mov_b32_e32 v36, v49
	v_mov_b32_e32 v35, v49
	v_mov_b32_e32 v34, v49
	s_branch .LBB0_921
.Ld5s_inactive:
	s_mul_i32 s23, s17, 0x4a00
	v_or_b32_e32 v252, s23, v129
	v_add_u32_e32 v253, v252, v131
	s_waitcnt vmcnt(3)
	ds_write_b128 v253, v[98:101]
	global_load_dwordx4 v[98:101], v228, s[12:13]
	v_add3_u32 v253, v252, v185, s33
	s_waitcnt vmcnt(2)
	ds_write2_b64 v253, v[102:103], v[104:105] offset1:1
	global_load_dwordx4 v[102:105], v230, s[24:25]
	v_add_u32_e32 v253, v252, v180
	s_waitcnt vmcnt(3)
	ds_write_b128 v253, v[106:109]
	global_load_dwordx4 v[106:109], v229, s[12:13]
	v_add3_u32 v253, v252, v186, s33
	s_waitcnt vmcnt(3)
	ds_write2_b64 v253, v[110:111], v[112:113] offset1:1
	global_load_dwordx4 v[110:113], v231, s[24:25]
	s_add_u32 s12, s12, 0x2000
	s_addc_u32 s13, s13, 0
	s_add_u32 s24, s24, 0x80
	s_addc_u32 s25, s25, 0
